# attention: K/V tile double-buffered in LDS (second tile in 16 KiB gap + 16 KiB static LDS), tile n+1 written while tile n is multiplied, one barrier per block
# baseline (speedup 1.0000x reference)
; #define LAS __attribute__((address_space(3)))
; #define LOADK(i) do { _Pragma("unroll") for (int j = 0; j < 4; ++j) st[j] = *(const u32x4*)(kbase + ((i) * 64 + j * 16) * 1024 + koff); } while (0)
; #define LOADV(i) do { _Pragma("unroll") for (int j = 0; j < 4; ++j) st[j] = *(const u32x4*)(vbase + (j * 64 * 256 + (i) * 64) + voff); } while (0)
; #define STOREK() do { _Pragma("unroll") for (int j = 0; j < 4; ++j) *(LAS u32x4*)(kst + j * 16 * 528) = st[j]; } while (0)
; __device__ __forceinline__ void ph_attn(const Params& p, LAS unsigned char* lds) {
;     ...
;         const bf16_t* kbase = kb + (size_t)kvb * 256 * 1024 + h * 256; const bf16_t* vbase = vt + ((size_t)kvb * 1024 + h * 256) * 256;
;     ...
;         f32x4 sc[16];
;         LOADK(0);
; #pragma unroll
;         for (int i = 0; i < 4; ++i) {
;             __syncthreads(); STOREK(); __syncthreads();
;             if (i < 3) LOADK(i + 1); else LOADV(0);
;             if (active) {
; #pragma unroll
;                 for (int sub = 0; sub < 4; ++sub) {
;                     f32x4 a = {0.f, 0.f, 0.f, 0.f};
; #pragma unroll
;                     for (int ks = 0; ks < 8; ++ks) {
;                         const bf16x8 kf = *(const LAS bf16x8*)(krd + sub * 16 * 528 + ks * 64);
;                         a = __builtin_amdgcn_mfma_f32_16x16x32_bf16(kf, qf[ks], a, 0, 0, 0);
;                     }
;                     sc[i * 4 + sub] = a;
;                 }
.LBB0_1092:
	s_ashr_i32 s5, s4, 31
	s_lshl_b64 s[16:17], s[4:5], 19
	s_add_u32 s18, s3, s16
	s_addc_u32 s19, s14, s17
	s_lshl_b64 s[4:5], s[10:11], 1
	s_add_u32 s98, s18, s4
	s_addc_u32 s99, s19, s5
	s_lshl_b64 s[18:19], s[10:11], 9
	s_add_u32 s100, s15, s16
	s_addc_u32 s101, s20, s17
	s_add_u32 s100, s100, s18
	s_addc_u32 s101, s101, s19
	v_lshlrev_b32_e32 v237, 1, v182
	v_lshlrev_b32_e32 v238, 1, v180
	v_xor_b32_e32 v124, 64, v193
	v_xor_b32_e32 v125, 0x80, v193
	v_xor_b32_e32 v126, 0xc0, v193
	v_add_u32_e32 v120, 0x19800, v193
	v_add_u32_e32 v121, 0x19800, v124
	v_add_u32_e32 v122, 0x19800, v125
	v_add_u32_e32 v123, 0x19800, v126
	v_add_u32_e32 v127, 0x19800, v202
	v_mov_b32_e32 v100, v237
	v_add_u32_e32 v104, 0x8000, v237
	v_add_u32_e32 v108, 0x10000, v237
	v_add_u32_e32 v112, 0x18000, v237
	global_load_dwordx4 v[100:103], v100, s[98:99]
	global_load_dwordx4 v[104:107], v104, s[98:99]
	global_load_dwordx4 v[108:111], v108, s[98:99]
	global_load_dwordx4 v[112:115], v112, s[98:99]
	v_add_u32_e32 v240, 0x20000, v237
	v_add_u32_e32 v244, 0x28000, v237
	v_add_u32_e32 v248, 0x30000, v237
	v_add_u32_e32 v252, 0x38000, v237
	global_load_dwordx4 v[240:243], v240, s[98:99]
	global_load_dwordx4 v[244:247], v244, s[98:99]
	global_load_dwordx4 v[248:251], v248, s[98:99]
	global_load_dwordx4 v[252:255], v252, s[98:99]
	s_waitcnt vmcnt(7)
	ds_write_b128 v202, v[100:103]
	s_waitcnt vmcnt(6)
	ds_write_b128 v202, v[104:107] offset:8192
	s_waitcnt vmcnt(5)
	ds_write_b128 v202, v[108:111] offset:16384
	s_waitcnt vmcnt(4)
	ds_write_b128 v202, v[112:115] offset:24576
	v_add_u32_e32 v100, 0x40000, v237
	v_add_u32_e32 v104, 0x48000, v237
	v_add_u32_e32 v108, 0x50000, v237
	v_add_u32_e32 v112, 0x58000, v237
	global_load_dwordx4 v[100:103], v100, s[98:99]
	global_load_dwordx4 v[104:107], v104, s[98:99]
	global_load_dwordx4 v[108:111], v108, s[98:99]
	global_load_dwordx4 v[112:115], v112, s[98:99]
	s_waitcnt lgkmcnt(0)
	s_barrier
	s_waitcnt vmcnt(7)
	ds_write_b128 v127, v[240:243]
	s_waitcnt vmcnt(6)
	ds_write_b128 v127, v[244:247] offset:8192
	s_waitcnt vmcnt(5)
	ds_write_b128 v127, v[248:251] offset:26640
	s_waitcnt vmcnt(4)
	ds_write_b128 v127, v[252:255] offset:34832
	v_add_u32_e32 v240, 0x60000, v237
	v_add_u32_e32 v244, 0x68000, v237
	v_add_u32_e32 v248, 0x70000, v237
	v_add_u32_e32 v252, 0x78000, v237
	global_load_dwordx4 v[240:243], v240, s[98:99]
	global_load_dwordx4 v[244:247], v244, s[98:99]
	global_load_dwordx4 v[248:251], v248, s[98:99]
	global_load_dwordx4 v[252:255], v252, s[98:99]
	s_and_b64 vcc, exec, s[12:13]
	s_cbranch_vccz .LBB0_1094
	ds_read_b128 v[128:131], v193
	ds_read_b128 v[132:135], v193 offset:8192
	ds_read_b128 v[136:139], v193 offset:16384
	ds_read_b128 v[140:143], v193 offset:24576
	ds_read_b128 v[144:147], v124
	ds_read_b128 v[148:151], v124 offset:8192
	ds_read_b128 v[152:155], v124 offset:16384
	ds_read_b128 v[156:159], v124 offset:24576
	s_waitcnt lgkmcnt(7)
	v_mfma_f32_16x16x32_bf16 v[48:51], v[128:131], v[32:35], 0
	ds_read_b128 v[160:163], v125
	s_waitcnt lgkmcnt(7)
	v_mfma_f32_16x16x32_bf16 v[64:67], v[132:135], v[32:35], 0
	ds_read_b128 v[164:167], v125 offset:8192
	s_waitcnt lgkmcnt(7)
	v_mfma_f32_16x16x32_bf16 v[80:83], v[136:139], v[32:35], 0
	ds_read_b128 v[168:171], v125 offset:16384
	s_waitcnt lgkmcnt(7)
	v_mfma_f32_16x16x32_bf16 v[96:99], v[140:143], v[32:35], 0
	ds_read_b128 v[172:175], v125 offset:24576
	s_waitcnt lgkmcnt(7)
	v_mfma_f32_16x16x32_bf16 v[48:51], v[144:147], v[28:31], v[48:51]
	ds_read_b128 v[176:179], v126
	s_waitcnt lgkmcnt(7)
	v_mfma_f32_16x16x32_bf16 v[64:67], v[148:151], v[28:31], v[64:67]
	ds_read_b128 v[128:131], v126 offset:8192
	s_waitcnt lgkmcnt(7)
	v_mfma_f32_16x16x32_bf16 v[80:83], v[152:155], v[28:31], v[80:83]
	ds_read_b128 v[132:135], v126 offset:16384
	s_waitcnt lgkmcnt(7)
	v_mfma_f32_16x16x32_bf16 v[96:99], v[156:159], v[28:31], v[96:99]
	ds_read_b128 v[136:139], v126 offset:24576
	s_waitcnt lgkmcnt(7)
	v_mfma_f32_16x16x32_bf16 v[48:51], v[160:163], v[24:27], v[48:51]
	ds_read_b128 v[140:143], v193 offset:256
	s_waitcnt lgkmcnt(7)
	v_mfma_f32_16x16x32_bf16 v[64:67], v[164:167], v[24:27], v[64:67]
	ds_read_b128 v[144:147], v193 offset:8448
	s_waitcnt lgkmcnt(7)
	v_mfma_f32_16x16x32_bf16 v[80:83], v[168:171], v[24:27], v[80:83]
	ds_read_b128 v[148:151], v193 offset:16640
	s_waitcnt lgkmcnt(7)
	v_mfma_f32_16x16x32_bf16 v[96:99], v[172:175], v[24:27], v[96:99]
	ds_read_b128 v[152:155], v193 offset:24832
	s_waitcnt lgkmcnt(7)
	v_mfma_f32_16x16x32_bf16 v[48:51], v[176:179], v[20:23], v[48:51]
	ds_read_b128 v[156:159], v124 offset:256
	s_waitcnt lgkmcnt(7)
	v_mfma_f32_16x16x32_bf16 v[64:67], v[128:131], v[20:23], v[64:67]
	ds_read_b128 v[160:163], v124 offset:8448
	s_waitcnt lgkmcnt(7)
	v_mfma_f32_16x16x32_bf16 v[80:83], v[132:135], v[20:23], v[80:83]
	ds_read_b128 v[164:167], v124 offset:16640
	s_waitcnt lgkmcnt(7)
	v_mfma_f32_16x16x32_bf16 v[96:99], v[136:139], v[20:23], v[96:99]
	ds_read_b128 v[168:171], v124 offset:24832
	s_waitcnt lgkmcnt(7)
	v_mfma_f32_16x16x32_bf16 v[48:51], v[140:143], v[16:19], v[48:51]
	ds_read_b128 v[172:175], v125 offset:256
	s_waitcnt lgkmcnt(7)
	v_mfma_f32_16x16x32_bf16 v[64:67], v[144:147], v[16:19], v[64:67]
	ds_read_b128 v[176:179], v125 offset:8448
	s_waitcnt lgkmcnt(7)
	v_mfma_f32_16x16x32_bf16 v[80:83], v[148:151], v[16:19], v[80:83]
	ds_read_b128 v[128:131], v125 offset:16640
	s_waitcnt lgkmcnt(7)
	v_mfma_f32_16x16x32_bf16 v[96:99], v[152:155], v[16:19], v[96:99]
	ds_read_b128 v[132:135], v125 offset:24832
	s_waitcnt lgkmcnt(7)
	v_mfma_f32_16x16x32_bf16 v[48:51], v[156:159], v[12:15], v[48:51]
	ds_read_b128 v[136:139], v126 offset:256
	s_waitcnt lgkmcnt(7)
	v_mfma_f32_16x16x32_bf16 v[64:67], v[160:163], v[12:15], v[64:67]
	ds_read_b128 v[140:143], v126 offset:8448
	s_waitcnt lgkmcnt(7)
	v_mfma_f32_16x16x32_bf16 v[80:83], v[164:167], v[12:15], v[80:83]
	ds_read_b128 v[144:147], v126 offset:16640
	s_waitcnt lgkmcnt(7)
	v_mfma_f32_16x16x32_bf16 v[96:99], v[168:171], v[12:15], v[96:99]
	ds_read_b128 v[148:151], v126 offset:24832
	s_waitcnt lgkmcnt(7)
	v_mfma_f32_16x16x32_bf16 v[48:51], v[172:175], v[8:11], v[48:51]
	s_waitcnt lgkmcnt(6)
	v_mfma_f32_16x16x32_bf16 v[64:67], v[176:179], v[8:11], v[64:67]
	s_waitcnt lgkmcnt(5)
	v_mfma_f32_16x16x32_bf16 v[80:83], v[128:131], v[8:11], v[80:83]
	s_waitcnt lgkmcnt(4)
	v_mfma_f32_16x16x32_bf16 v[96:99], v[132:135], v[8:11], v[96:99]
	s_waitcnt lgkmcnt(3)
	v_mfma_f32_16x16x32_bf16 v[48:51], v[136:139], v[4:7], v[48:51]
	s_waitcnt lgkmcnt(2)
	v_mfma_f32_16x16x32_bf16 v[64:67], v[140:143], v[4:7], v[64:67]
	s_waitcnt lgkmcnt(1)
	v_mfma_f32_16x16x32_bf16 v[80:83], v[144:147], v[4:7], v[80:83]
	s_waitcnt lgkmcnt(0)
	v_mfma_f32_16x16x32_bf16 v[96:99], v[148:151], v[4:7], v[96:99]
; #define LAS __attribute__((address_space(3)))
; #define LOADK(i) do { _Pragma("unroll") for (int j = 0; j < 4; ++j) st[j] = *(const u32x4*)(kbase + ((i) * 64 + j * 16) * 1024 + koff); } while (0)
; #define LOADV(i) do { _Pragma("unroll") for (int j = 0; j < 4; ++j) st[j] = *(const u32x4*)(vbase + (j * 64 * 256 + (i) * 64) + voff); } while (0)
; #define STOREK() do { _Pragma("unroll") for (int j = 0; j < 4; ++j) *(LAS u32x4*)(kst + j * 16 * 528) = st[j]; } while (0)
; __device__ __forceinline__ void ph_attn(const Params& p, LAS unsigned char* lds) {
;     ...
;         f32x4 sc[16];
;         LOADK(0);
; #pragma unroll
;         for (int i = 0; i < 4; ++i) {
;             __syncthreads(); STOREK(); __syncthreads();
;             if (i < 3) LOADK(i + 1); else LOADV(0);
;             if (active) {
; #pragma unroll
;                 for (int sub = 0; sub < 4; ++sub) {
;                     f32x4 a = {0.f, 0.f, 0.f, 0.f};
; #pragma unroll
;                     for (int ks = 0; ks < 8; ++ks) {
;                         const bf16x8 kf = *(const LAS bf16x8*)(krd + sub * 16 * 528 + ks * 64);
;                         a = __builtin_amdgcn_mfma_f32_16x16x32_bf16(kf, qf[ks], a, 0, 0, 0);
;                     }
;                     sc[i * 4 + sub] = a;
;                 }
.LBB0_1094:
	s_waitcnt lgkmcnt(0)
	s_barrier
	s_waitcnt vmcnt(7)
	ds_write_b128 v202, v[100:103]
	s_waitcnt vmcnt(6)
	ds_write_b128 v202, v[104:107] offset:8192
	s_waitcnt vmcnt(5)
	ds_write_b128 v202, v[108:111] offset:16384
	s_waitcnt vmcnt(4)
	ds_write_b128 v202, v[112:115] offset:24576
	v_mov_b32_e32 v100, v238
	v_add_u32_e32 v104, 0x8000, v238
	v_add_u32_e32 v108, 0x10000, v238
	v_add_u32_e32 v112, 0x18000, v238
	global_load_dwordx4 v[100:103], v100, s[100:101]
	global_load_dwordx4 v[104:107], v104, s[100:101]
	global_load_dwordx4 v[108:111], v108, s[100:101]
	global_load_dwordx4 v[112:115], v112, s[100:101]
	v_cndmask_b32_e64 v1, 0, 1, s[12:13]
	v_cmp_ne_u32_e64 s[4:5], 1, v1
	s_andn2_b64 vcc, exec, s[12:13]
	s_cbranch_vccnz .LBB0_1096
	ds_read_b128 v[128:131], v120
	ds_read_b128 v[132:135], v120 offset:8192
	ds_read_b128 v[136:139], v120 offset:26640
	ds_read_b128 v[140:143], v120 offset:34832
	ds_read_b128 v[144:147], v121
	ds_read_b128 v[148:151], v121 offset:8192
	ds_read_b128 v[152:155], v121 offset:26640
	ds_read_b128 v[156:159], v121 offset:34832
	s_waitcnt lgkmcnt(7)
	v_mfma_f32_16x16x32_bf16 v[44:47], v[128:131], v[32:35], 0
	ds_read_b128 v[160:163], v122
	s_waitcnt lgkmcnt(7)
	v_mfma_f32_16x16x32_bf16 v[60:63], v[132:135], v[32:35], 0
	ds_read_b128 v[164:167], v122 offset:8192
	s_waitcnt lgkmcnt(7)
	v_mfma_f32_16x16x32_bf16 v[76:79], v[136:139], v[32:35], 0
	ds_read_b128 v[168:171], v122 offset:26640
	s_waitcnt lgkmcnt(7)
	v_mfma_f32_16x16x32_bf16 v[92:95], v[140:143], v[32:35], 0
	ds_read_b128 v[172:175], v122 offset:34832
	s_waitcnt lgkmcnt(7)
	v_mfma_f32_16x16x32_bf16 v[44:47], v[144:147], v[28:31], v[44:47]
	ds_read_b128 v[176:179], v123
	s_waitcnt lgkmcnt(7)
	v_mfma_f32_16x16x32_bf16 v[60:63], v[148:151], v[28:31], v[60:63]
	ds_read_b128 v[128:131], v123 offset:8192
	s_waitcnt lgkmcnt(7)
	v_mfma_f32_16x16x32_bf16 v[76:79], v[152:155], v[28:31], v[76:79]
	ds_read_b128 v[132:135], v123 offset:26640
	s_waitcnt lgkmcnt(7)
	v_mfma_f32_16x16x32_bf16 v[92:95], v[156:159], v[28:31], v[92:95]
	ds_read_b128 v[136:139], v123 offset:34832
	s_waitcnt lgkmcnt(7)
	v_mfma_f32_16x16x32_bf16 v[44:47], v[160:163], v[24:27], v[44:47]
	ds_read_b128 v[140:143], v120 offset:256
	s_waitcnt lgkmcnt(7)
	v_mfma_f32_16x16x32_bf16 v[60:63], v[164:167], v[24:27], v[60:63]
	ds_read_b128 v[144:147], v120 offset:8448
	s_waitcnt lgkmcnt(7)
	v_mfma_f32_16x16x32_bf16 v[76:79], v[168:171], v[24:27], v[76:79]
	ds_read_b128 v[148:151], v120 offset:26896
	s_waitcnt lgkmcnt(7)
	v_mfma_f32_16x16x32_bf16 v[92:95], v[172:175], v[24:27], v[92:95]
	ds_read_b128 v[152:155], v120 offset:35088
	s_waitcnt lgkmcnt(7)
	v_mfma_f32_16x16x32_bf16 v[44:47], v[176:179], v[20:23], v[44:47]
	ds_read_b128 v[156:159], v121 offset:256
	s_waitcnt lgkmcnt(7)
	v_mfma_f32_16x16x32_bf16 v[60:63], v[128:131], v[20:23], v[60:63]
	ds_read_b128 v[160:163], v121 offset:8448
	s_waitcnt lgkmcnt(7)
	v_mfma_f32_16x16x32_bf16 v[76:79], v[132:135], v[20:23], v[76:79]
	ds_read_b128 v[164:167], v121 offset:26896
	s_waitcnt lgkmcnt(7)
	v_mfma_f32_16x16x32_bf16 v[92:95], v[136:139], v[20:23], v[92:95]
	ds_read_b128 v[168:171], v121 offset:35088
	s_waitcnt lgkmcnt(7)
	v_mfma_f32_16x16x32_bf16 v[44:47], v[140:143], v[16:19], v[44:47]
	ds_read_b128 v[172:175], v122 offset:256
	s_waitcnt lgkmcnt(7)
	v_mfma_f32_16x16x32_bf16 v[60:63], v[144:147], v[16:19], v[60:63]
	ds_read_b128 v[176:179], v122 offset:8448
	s_waitcnt lgkmcnt(7)
	v_mfma_f32_16x16x32_bf16 v[76:79], v[148:151], v[16:19], v[76:79]
	ds_read_b128 v[128:131], v122 offset:26896
	s_waitcnt lgkmcnt(7)
	v_mfma_f32_16x16x32_bf16 v[92:95], v[152:155], v[16:19], v[92:95]
	ds_read_b128 v[132:135], v122 offset:35088
	s_waitcnt lgkmcnt(7)
	v_mfma_f32_16x16x32_bf16 v[44:47], v[156:159], v[12:15], v[44:47]
	ds_read_b128 v[136:139], v123 offset:256
	s_waitcnt lgkmcnt(7)
	v_mfma_f32_16x16x32_bf16 v[60:63], v[160:163], v[12:15], v[60:63]
	ds_read_b128 v[140:143], v123 offset:8448
	s_waitcnt lgkmcnt(7)
	v_mfma_f32_16x16x32_bf16 v[76:79], v[164:167], v[12:15], v[76:79]
	ds_read_b128 v[144:147], v123 offset:26896
	s_waitcnt lgkmcnt(7)
	v_mfma_f32_16x16x32_bf16 v[92:95], v[168:171], v[12:15], v[92:95]
	ds_read_b128 v[148:151], v123 offset:35088
	s_waitcnt lgkmcnt(7)
	v_mfma_f32_16x16x32_bf16 v[44:47], v[172:175], v[8:11], v[44:47]
	s_waitcnt lgkmcnt(6)
	v_mfma_f32_16x16x32_bf16 v[60:63], v[176:179], v[8:11], v[60:63]
	s_waitcnt lgkmcnt(5)
	v_mfma_f32_16x16x32_bf16 v[76:79], v[128:131], v[8:11], v[76:79]
	s_waitcnt lgkmcnt(4)
	v_mfma_f32_16x16x32_bf16 v[92:95], v[132:135], v[8:11], v[92:95]
	s_waitcnt lgkmcnt(3)
	v_mfma_f32_16x16x32_bf16 v[44:47], v[136:139], v[4:7], v[44:47]
	s_waitcnt lgkmcnt(2)
	v_mfma_f32_16x16x32_bf16 v[60:63], v[140:143], v[4:7], v[60:63]
	s_waitcnt lgkmcnt(1)
	v_mfma_f32_16x16x32_bf16 v[76:79], v[144:147], v[4:7], v[76:79]
	s_waitcnt lgkmcnt(0)
	v_mfma_f32_16x16x32_bf16 v[92:95], v[148:151], v[4:7], v[92:95]
; #define LAS __attribute__((address_space(3)))
; #define LOADK(i) do { _Pragma("unroll") for (int j = 0; j < 4; ++j) st[j] = *(const u32x4*)(kbase + ((i) * 64 + j * 16) * 1024 + koff); } while (0)
; #define LOADV(i) do { _Pragma("unroll") for (int j = 0; j < 4; ++j) st[j] = *(const u32x4*)(vbase + (j * 64 * 256 + (i) * 64) + voff); } while (0)
; #define STOREK() do { _Pragma("unroll") for (int j = 0; j < 4; ++j) *(LAS u32x4*)(kst + j * 16 * 528) = st[j]; } while (0)
; __device__ __forceinline__ void ph_attn(const Params& p, LAS unsigned char* lds) {
;     ...
;         f32x4 sc[16];
;         LOADK(0);
; #pragma unroll
;         for (int i = 0; i < 4; ++i) {
;             __syncthreads(); STOREK(); __syncthreads();
;             if (i < 3) LOADK(i + 1); else LOADV(0);
;             if (active) {
; #pragma unroll
;                 for (int sub = 0; sub < 4; ++sub) {
;                     f32x4 a = {0.f, 0.f, 0.f, 0.f};
; #pragma unroll
;                     for (int ks = 0; ks < 8; ++ks) {
;                         const bf16x8 kf = *(const LAS bf16x8*)(krd + sub * 16 * 528 + ks * 64);
;                         a = __builtin_amdgcn_mfma_f32_16x16x32_bf16(kf, qf[ks], a, 0, 0, 0);
;                     }
;                     sc[i * 4 + sub] = a;
;                 }
.LBB0_1096:
	s_waitcnt lgkmcnt(0)
	s_barrier
	s_waitcnt vmcnt(7)
	ds_write_b128 v127, v[240:243]
	s_waitcnt vmcnt(6)
	ds_write_b128 v127, v[244:247] offset:8192
	s_waitcnt vmcnt(5)
	ds_write_b128 v127, v[248:251] offset:26640
	s_waitcnt vmcnt(4)
	ds_write_b128 v127, v[252:255] offset:34832
	v_mov_b32_e32 v240, v238
	v_add_u32_e32 v244, 0x8000, v238
	v_add_u32_e32 v248, 0x10000, v238
	v_add_u32_e32 v252, 0x18000, v238
	global_load_dwordx4 v[240:243], v240, s[100:101] offset:128
	global_load_dwordx4 v[244:247], v244, s[100:101] offset:128
	global_load_dwordx4 v[248:251], v248, s[100:101] offset:128
	global_load_dwordx4 v[252:255], v252, s[100:101] offset:128
	s_and_b64 vcc, exec, s[4:5]
	s_cbranch_vccnz .LBB0_1098
	ds_read_b128 v[128:131], v193
	ds_read_b128 v[132:135], v193 offset:8192
	ds_read_b128 v[136:139], v193 offset:16384
	ds_read_b128 v[140:143], v193 offset:24576
	ds_read_b128 v[144:147], v124
	ds_read_b128 v[148:151], v124 offset:8192
	ds_read_b128 v[152:155], v124 offset:16384
	ds_read_b128 v[156:159], v124 offset:24576
	s_waitcnt lgkmcnt(7)
	v_mfma_f32_16x16x32_bf16 v[40:43], v[128:131], v[32:35], 0
	ds_read_b128 v[160:163], v125
	s_waitcnt lgkmcnt(7)
	v_mfma_f32_16x16x32_bf16 v[56:59], v[132:135], v[32:35], 0
	ds_read_b128 v[164:167], v125 offset:8192
	s_waitcnt lgkmcnt(7)
	v_mfma_f32_16x16x32_bf16 v[72:75], v[136:139], v[32:35], 0
	ds_read_b128 v[168:171], v125 offset:16384
	s_waitcnt lgkmcnt(7)
	v_mfma_f32_16x16x32_bf16 v[88:91], v[140:143], v[32:35], 0
	ds_read_b128 v[172:175], v125 offset:24576
	s_waitcnt lgkmcnt(7)
	v_mfma_f32_16x16x32_bf16 v[40:43], v[144:147], v[28:31], v[40:43]
	ds_read_b128 v[176:179], v126
	s_waitcnt lgkmcnt(7)
	v_mfma_f32_16x16x32_bf16 v[56:59], v[148:151], v[28:31], v[56:59]
	ds_read_b128 v[128:131], v126 offset:8192
	s_waitcnt lgkmcnt(7)
	v_mfma_f32_16x16x32_bf16 v[72:75], v[152:155], v[28:31], v[72:75]
	ds_read_b128 v[132:135], v126 offset:16384
	s_waitcnt lgkmcnt(7)
	v_mfma_f32_16x16x32_bf16 v[88:91], v[156:159], v[28:31], v[88:91]
	ds_read_b128 v[136:139], v126 offset:24576
	s_waitcnt lgkmcnt(7)
	v_mfma_f32_16x16x32_bf16 v[40:43], v[160:163], v[24:27], v[40:43]
	ds_read_b128 v[140:143], v193 offset:256
	s_waitcnt lgkmcnt(7)
	v_mfma_f32_16x16x32_bf16 v[56:59], v[164:167], v[24:27], v[56:59]
	ds_read_b128 v[144:147], v193 offset:8448
	s_waitcnt lgkmcnt(7)
	v_mfma_f32_16x16x32_bf16 v[72:75], v[168:171], v[24:27], v[72:75]
	ds_read_b128 v[148:151], v193 offset:16640
	s_waitcnt lgkmcnt(7)
	v_mfma_f32_16x16x32_bf16 v[88:91], v[172:175], v[24:27], v[88:91]
	ds_read_b128 v[152:155], v193 offset:24832
	s_waitcnt lgkmcnt(7)
	v_mfma_f32_16x16x32_bf16 v[40:43], v[176:179], v[20:23], v[40:43]
	ds_read_b128 v[156:159], v124 offset:256
	s_waitcnt lgkmcnt(7)
	v_mfma_f32_16x16x32_bf16 v[56:59], v[128:131], v[20:23], v[56:59]
	ds_read_b128 v[160:163], v124 offset:8448
	s_waitcnt lgkmcnt(7)
	v_mfma_f32_16x16x32_bf16 v[72:75], v[132:135], v[20:23], v[72:75]
	ds_read_b128 v[164:167], v124 offset:16640
	s_waitcnt lgkmcnt(7)
	v_mfma_f32_16x16x32_bf16 v[88:91], v[136:139], v[20:23], v[88:91]
	ds_read_b128 v[168:171], v124 offset:24832
	s_waitcnt lgkmcnt(7)
	v_mfma_f32_16x16x32_bf16 v[40:43], v[140:143], v[16:19], v[40:43]
	ds_read_b128 v[172:175], v125 offset:256
	s_waitcnt lgkmcnt(7)
	v_mfma_f32_16x16x32_bf16 v[56:59], v[144:147], v[16:19], v[56:59]
	ds_read_b128 v[176:179], v125 offset:8448
	s_waitcnt lgkmcnt(7)
	v_mfma_f32_16x16x32_bf16 v[72:75], v[148:151], v[16:19], v[72:75]
	ds_read_b128 v[128:131], v125 offset:16640
	s_waitcnt lgkmcnt(7)
	v_mfma_f32_16x16x32_bf16 v[88:91], v[152:155], v[16:19], v[88:91]
	ds_read_b128 v[132:135], v125 offset:24832
	s_waitcnt lgkmcnt(7)
	v_mfma_f32_16x16x32_bf16 v[40:43], v[156:159], v[12:15], v[40:43]
	ds_read_b128 v[136:139], v126 offset:256
	s_waitcnt lgkmcnt(7)
	v_mfma_f32_16x16x32_bf16 v[56:59], v[160:163], v[12:15], v[56:59]
	ds_read_b128 v[140:143], v126 offset:8448
	s_waitcnt lgkmcnt(7)
	v_mfma_f32_16x16x32_bf16 v[72:75], v[164:167], v[12:15], v[72:75]
	ds_read_b128 v[144:147], v126 offset:16640
	s_waitcnt lgkmcnt(7)
	v_mfma_f32_16x16x32_bf16 v[88:91], v[168:171], v[12:15], v[88:91]
	ds_read_b128 v[148:151], v126 offset:24832
	s_waitcnt lgkmcnt(7)
	v_mfma_f32_16x16x32_bf16 v[40:43], v[172:175], v[8:11], v[40:43]
	s_waitcnt lgkmcnt(6)
	v_mfma_f32_16x16x32_bf16 v[56:59], v[176:179], v[8:11], v[56:59]
	s_waitcnt lgkmcnt(5)
	v_mfma_f32_16x16x32_bf16 v[72:75], v[128:131], v[8:11], v[72:75]
	s_waitcnt lgkmcnt(4)
	v_mfma_f32_16x16x32_bf16 v[88:91], v[132:135], v[8:11], v[88:91]
	s_waitcnt lgkmcnt(3)
	v_mfma_f32_16x16x32_bf16 v[40:43], v[136:139], v[4:7], v[40:43]
	s_waitcnt lgkmcnt(2)
	v_mfma_f32_16x16x32_bf16 v[56:59], v[140:143], v[4:7], v[56:59]
	s_waitcnt lgkmcnt(1)
	v_mfma_f32_16x16x32_bf16 v[72:75], v[144:147], v[4:7], v[72:75]
	s_waitcnt lgkmcnt(0)
	v_mfma_f32_16x16x32_bf16 v[88:91], v[148:151], v[4:7], v[88:91]
; #define LAS __attribute__((address_space(3)))
; #define LOADK(i) do { _Pragma("unroll") for (int j = 0; j < 4; ++j) st[j] = *(const u32x4*)(kbase + ((i) * 64 + j * 16) * 1024 + koff); } while (0)
; #define LOADV(i) do { _Pragma("unroll") for (int j = 0; j < 4; ++j) st[j] = *(const u32x4*)(vbase + (j * 64 * 256 + (i) * 64) + voff); } while (0)
; #define STOREK() do { _Pragma("unroll") for (int j = 0; j < 4; ++j) *(LAS u32x4*)(kst + j * 16 * 528) = st[j]; } while (0)
; __device__ __forceinline__ void ph_attn(const Params& p, LAS unsigned char* lds) {
;     ...
;         f32x4 sc[16];
;         LOADK(0);
; #pragma unroll
;         for (int i = 0; i < 4; ++i) {
;             __syncthreads(); STOREK(); __syncthreads();
;             if (i < 3) LOADK(i + 1); else LOADV(0);
;             if (active) {
; #pragma unroll
;                 for (int sub = 0; sub < 4; ++sub) {
;                     f32x4 a = {0.f, 0.f, 0.f, 0.f};
; #pragma unroll
;                     for (int ks = 0; ks < 8; ++ks) {
;                         const bf16x8 kf = *(const LAS bf16x8*)(krd + sub * 16 * 528 + ks * 64);
;                         a = __builtin_amdgcn_mfma_f32_16x16x32_bf16(kf, qf[ks], a, 0, 0, 0);
;                     }
;                     sc[i * 4 + sub] = a;
;                 }
.LBB0_1098:
	s_lshl_b64 s[18:19], s[10:11], 9
	s_add_u32 s28, s15, s16
	s_addc_u32 s29, s20, s17
	s_add_u32 s28, s28, s18
	s_addc_u32 s29, s29, s19
	s_waitcnt lgkmcnt(0)
	s_barrier
	s_waitcnt vmcnt(7)
	ds_write_b128 v199, v[100:103]
	s_waitcnt vmcnt(6)
	ds_write_b128 v199, v[104:107] offset:8192
	s_waitcnt vmcnt(5)
	ds_write_b128 v199, v[108:111] offset:16384
	s_waitcnt vmcnt(4)
	ds_write_b128 v199, v[112:115] offset:24576
	v_mov_b32_e32 v100, v238
	v_add_u32_e32 v104, 0x8000, v238
	v_add_u32_e32 v108, 0x10000, v238
	v_add_u32_e32 v112, 0x18000, v238
	global_load_dwordx4 v[100:103], v100, s[100:101] offset:256
	global_load_dwordx4 v[104:107], v104, s[100:101] offset:256
	global_load_dwordx4 v[108:111], v108, s[100:101] offset:256
	global_load_dwordx4 v[112:115], v112, s[100:101] offset:256
	s_and_b64 vcc, exec, s[4:5]
	s_cbranch_vccnz .LBB0_1100
	ds_read_b128 v[128:131], v120
	ds_read_b128 v[132:135], v120 offset:8192
	ds_read_b128 v[136:139], v120 offset:26640
	ds_read_b128 v[140:143], v120 offset:34832
	ds_read_b128 v[144:147], v121
	ds_read_b128 v[148:151], v121 offset:8192
	ds_read_b128 v[152:155], v121 offset:26640
	ds_read_b128 v[156:159], v121 offset:34832
	s_waitcnt lgkmcnt(7)
	v_mfma_f32_16x16x32_bf16 v[36:39], v[128:131], v[32:35], 0
	ds_read_b128 v[160:163], v122
	s_waitcnt lgkmcnt(7)
	v_mfma_f32_16x16x32_bf16 v[52:55], v[132:135], v[32:35], 0
	ds_read_b128 v[164:167], v122 offset:8192
	s_waitcnt lgkmcnt(7)
	v_mfma_f32_16x16x32_bf16 v[68:71], v[136:139], v[32:35], 0
	ds_read_b128 v[168:171], v122 offset:26640
	s_waitcnt lgkmcnt(7)
	v_mfma_f32_16x16x32_bf16 v[84:87], v[140:143], v[32:35], 0
	ds_read_b128 v[172:175], v122 offset:34832
	s_waitcnt lgkmcnt(7)
	v_mfma_f32_16x16x32_bf16 v[36:39], v[144:147], v[28:31], v[36:39]
	ds_read_b128 v[176:179], v123
	s_waitcnt lgkmcnt(7)
	v_mfma_f32_16x16x32_bf16 v[52:55], v[148:151], v[28:31], v[52:55]
	ds_read_b128 v[128:131], v123 offset:8192
	s_waitcnt lgkmcnt(7)
	v_mfma_f32_16x16x32_bf16 v[68:71], v[152:155], v[28:31], v[68:71]
	ds_read_b128 v[132:135], v123 offset:26640
	s_waitcnt lgkmcnt(7)
	v_mfma_f32_16x16x32_bf16 v[84:87], v[156:159], v[28:31], v[84:87]
	ds_read_b128 v[136:139], v123 offset:34832
	s_waitcnt lgkmcnt(7)
	v_mfma_f32_16x16x32_bf16 v[36:39], v[160:163], v[24:27], v[36:39]
	ds_read_b128 v[140:143], v120 offset:256
	s_waitcnt lgkmcnt(7)
	v_mfma_f32_16x16x32_bf16 v[52:55], v[164:167], v[24:27], v[52:55]
	ds_read_b128 v[144:147], v120 offset:8448
	s_waitcnt lgkmcnt(7)
	v_mfma_f32_16x16x32_bf16 v[68:71], v[168:171], v[24:27], v[68:71]
	ds_read_b128 v[148:151], v120 offset:26896
	s_waitcnt lgkmcnt(7)
	v_mfma_f32_16x16x32_bf16 v[84:87], v[172:175], v[24:27], v[84:87]
	ds_read_b128 v[152:155], v120 offset:35088
	s_waitcnt lgkmcnt(7)
	v_mfma_f32_16x16x32_bf16 v[36:39], v[176:179], v[20:23], v[36:39]
	ds_read_b128 v[156:159], v121 offset:256
	s_waitcnt lgkmcnt(7)
	v_mfma_f32_16x16x32_bf16 v[52:55], v[128:131], v[20:23], v[52:55]
	ds_read_b128 v[160:163], v121 offset:8448
	s_waitcnt lgkmcnt(7)
	v_mfma_f32_16x16x32_bf16 v[68:71], v[132:135], v[20:23], v[68:71]
	ds_read_b128 v[164:167], v121 offset:26896
	s_waitcnt lgkmcnt(7)
	v_mfma_f32_16x16x32_bf16 v[84:87], v[136:139], v[20:23], v[84:87]
	ds_read_b128 v[168:171], v121 offset:35088
	s_waitcnt lgkmcnt(7)
	v_mfma_f32_16x16x32_bf16 v[36:39], v[140:143], v[16:19], v[36:39]
	ds_read_b128 v[172:175], v122 offset:256
	s_waitcnt lgkmcnt(7)
	v_mfma_f32_16x16x32_bf16 v[52:55], v[144:147], v[16:19], v[52:55]
	ds_read_b128 v[176:179], v122 offset:8448
	s_waitcnt lgkmcnt(7)
	v_mfma_f32_16x16x32_bf16 v[68:71], v[148:151], v[16:19], v[68:71]
	ds_read_b128 v[128:131], v122 offset:26896
	s_waitcnt lgkmcnt(7)
	v_mfma_f32_16x16x32_bf16 v[84:87], v[152:155], v[16:19], v[84:87]
	ds_read_b128 v[132:135], v122 offset:35088
	s_waitcnt lgkmcnt(7)
	v_mfma_f32_16x16x32_bf16 v[36:39], v[156:159], v[12:15], v[36:39]
	ds_read_b128 v[136:139], v123 offset:256
	s_waitcnt lgkmcnt(7)
	v_mfma_f32_16x16x32_bf16 v[52:55], v[160:163], v[12:15], v[52:55]
	ds_read_b128 v[140:143], v123 offset:8448
	s_waitcnt lgkmcnt(7)
	v_mfma_f32_16x16x32_bf16 v[68:71], v[164:167], v[12:15], v[68:71]
	ds_read_b128 v[144:147], v123 offset:26896
	s_waitcnt lgkmcnt(7)
	v_mfma_f32_16x16x32_bf16 v[84:87], v[168:171], v[12:15], v[84:87]
	ds_read_b128 v[148:151], v123 offset:35088
	s_waitcnt lgkmcnt(7)
	v_mfma_f32_16x16x32_bf16 v[36:39], v[172:175], v[8:11], v[36:39]
	s_waitcnt lgkmcnt(6)
	v_mfma_f32_16x16x32_bf16 v[52:55], v[176:179], v[8:11], v[52:55]
	s_waitcnt lgkmcnt(5)
	v_mfma_f32_16x16x32_bf16 v[68:71], v[128:131], v[8:11], v[68:71]
	s_waitcnt lgkmcnt(4)
	v_mfma_f32_16x16x32_bf16 v[84:87], v[132:135], v[8:11], v[84:87]
	s_waitcnt lgkmcnt(3)
	v_mfma_f32_16x16x32_bf16 v[36:39], v[136:139], v[4:7], v[36:39]
	s_waitcnt lgkmcnt(2)
	v_mfma_f32_16x16x32_bf16 v[52:55], v[140:143], v[4:7], v[52:55]
	s_waitcnt lgkmcnt(1)
	v_mfma_f32_16x16x32_bf16 v[68:71], v[144:147], v[4:7], v[68:71]
	s_waitcnt lgkmcnt(0)
	v_mfma_f32_16x16x32_bf16 v[84:87], v[148:151], v[4:7], v[84:87]

; #define LAS __attribute__((address_space(3)))
; #define LOADV(i) do { _Pragma("unroll") for (int j = 0; j < 4; ++j) st[j] = *(const u32x4*)(vbase + (j * 64 * 256 + (i) * 64) + voff); } while (0)
; #define STOREV() do { _Pragma("unroll") for (int j = 0; j < 4; ++j) *(LAS u32x4*)(vst + j * 64 * 144) = st[j]; } while (0)
; __device__ __forceinline__ void ph_attn(const Params& p, LAS unsigned char* lds) {
;     ...
; #pragma unroll 1
;         for (int i = 0; i < 4; ++i) {
;             __syncthreads(); STOREV(); __syncthreads();
;             if (i < 3) LOADV(i + 1);
;             if (active) {
; #pragma unroll
;                 for (int ks = 0; ks < 2; ++ks) {
;                     const bf16x8 pf = *(const LAS bf16x8*)(pw + fq * 8 + i * 128 + ks * 64);
; #pragma unroll
;                     for (int dt = 0; dt < 16; ++dt) {
;                         const bf16x8 vf = *(const LAS bf16x8*)(vrd + dt * 16 * 144 + ks * 64);
;                         oa[dt] = __builtin_amdgcn_mfma_f32_16x16x32_bf16(vf, pf, oa[dt], 0, 0, 0);
;                     }
;                 }
.LBB0_1104:
	v_add_u32_e32 v4, 0x19800, v201
	v_add_u32_e32 v5, 0x19800, v239
	v_add_u32_e32 v6, 0x19800, v199
	s_waitcnt lgkmcnt(0)
	s_barrier
	s_waitcnt vmcnt(7)
	ds_write_b128 v6, v[240:243]
	s_waitcnt vmcnt(6)
	ds_write_b128 v6, v[244:247] offset:8192
	s_waitcnt vmcnt(5)
	ds_write_b128 v6, v[248:251] offset:26640
	s_waitcnt vmcnt(4)
	ds_write_b128 v6, v[252:255] offset:34832
	v_mov_b32_e32 v240, v238
	v_add_u32_e32 v244, 0x8000, v238
	v_add_u32_e32 v248, 0x10000, v238
	v_add_u32_e32 v252, 0x18000, v238
	global_load_dwordx4 v[240:243], v240, s[100:101] offset:384
	global_load_dwordx4 v[244:247], v244, s[100:101] offset:384
	global_load_dwordx4 v[248:251], v248, s[100:101] offset:384
	global_load_dwordx4 v[252:255], v252, s[100:101] offset:384
	s_and_b64 vcc, exec, s[4:5]
	s_cbranch_vccnz .Lat_pv1
	ds_read_b128 v[208:211], v187
	ds_read_b128 v[212:215], v187 offset:64
	ds_read_b128 v[36:39], v201
	ds_read_b128 v[40:43], v201 offset:2048
	ds_read_b128 v[44:47], v201 offset:4096
	ds_read_b128 v[48:51], v201 offset:6144
	ds_read_b128 v[52:55], v201 offset:8192
	ds_read_b128 v[56:59], v201 offset:10240
	ds_read_b128 v[60:63], v201 offset:12288
	ds_read_b128 v[64:67], v201 offset:14336
	s_waitcnt lgkmcnt(7)
	v_mfma_f32_16x16x32_bf16 v[176:179], v[36:39], v[208:211], v[176:179]
	ds_read_b128 v[68:71], v201 offset:16384
	s_waitcnt lgkmcnt(7)
	v_mfma_f32_16x16x32_bf16 v[172:175], v[40:43], v[208:211], v[172:175]
	ds_read_b128 v[72:75], v201 offset:18432
	s_waitcnt lgkmcnt(7)
	v_mfma_f32_16x16x32_bf16 v[168:171], v[44:47], v[208:211], v[168:171]
	ds_read_b128 v[76:79], v201 offset:20480
	s_waitcnt lgkmcnt(7)
	v_mfma_f32_16x16x32_bf16 v[164:167], v[48:51], v[208:211], v[164:167]
	ds_read_b128 v[80:83], v201 offset:22528
	s_waitcnt lgkmcnt(7)
	v_mfma_f32_16x16x32_bf16 v[160:163], v[52:55], v[208:211], v[160:163]
	ds_read_b128 v[84:87], v201 offset:24576
	s_waitcnt lgkmcnt(7)
	v_mfma_f32_16x16x32_bf16 v[156:159], v[56:59], v[208:211], v[156:159]
	ds_read_b128 v[88:91], v201 offset:26624
	s_waitcnt lgkmcnt(7)
	v_mfma_f32_16x16x32_bf16 v[152:155], v[60:63], v[208:211], v[152:155]
	ds_read_b128 v[92:95], v201 offset:28672
	s_waitcnt lgkmcnt(7)
	v_mfma_f32_16x16x32_bf16 v[148:151], v[64:67], v[208:211], v[148:151]
	ds_read_b128 v[96:99], v201 offset:30720
	s_waitcnt lgkmcnt(7)
	v_mfma_f32_16x16x32_bf16 v[144:147], v[68:71], v[208:211], v[144:147]
	ds_read_b128 v[36:39], v239
	s_waitcnt lgkmcnt(7)
	v_mfma_f32_16x16x32_bf16 v[140:143], v[72:75], v[208:211], v[140:143]
	ds_read_b128 v[40:43], v239 offset:2048
	s_waitcnt lgkmcnt(7)
	v_mfma_f32_16x16x32_bf16 v[136:139], v[76:79], v[208:211], v[136:139]
	ds_read_b128 v[44:47], v239 offset:4096
	s_waitcnt lgkmcnt(7)
	v_mfma_f32_16x16x32_bf16 v[132:135], v[80:83], v[208:211], v[132:135]
	ds_read_b128 v[48:51], v239 offset:6144
	s_waitcnt lgkmcnt(7)
	v_mfma_f32_16x16x32_bf16 v[128:131], v[84:87], v[208:211], v[128:131]
	ds_read_b128 v[52:55], v239 offset:8192
	s_waitcnt lgkmcnt(7)
	v_mfma_f32_16x16x32_bf16 v[124:127], v[88:91], v[208:211], v[124:127]
	ds_read_b128 v[56:59], v239 offset:10240
	s_waitcnt lgkmcnt(7)
	v_mfma_f32_16x16x32_bf16 v[120:123], v[92:95], v[208:211], v[120:123]
	ds_read_b128 v[60:63], v239 offset:12288
	s_waitcnt lgkmcnt(7)
	v_mfma_f32_16x16x32_bf16 v[116:119], v[96:99], v[208:211], v[116:119]
	ds_read_b128 v[64:67], v239 offset:14336
	s_waitcnt lgkmcnt(7)
	v_mfma_f32_16x16x32_bf16 v[176:179], v[36:39], v[212:215], v[176:179]
	ds_read_b128 v[68:71], v239 offset:16384
	s_waitcnt lgkmcnt(7)
	v_mfma_f32_16x16x32_bf16 v[172:175], v[40:43], v[212:215], v[172:175]
	ds_read_b128 v[72:75], v239 offset:18432
	s_waitcnt lgkmcnt(7)
	v_mfma_f32_16x16x32_bf16 v[168:171], v[44:47], v[212:215], v[168:171]
	ds_read_b128 v[76:79], v239 offset:20480
	s_waitcnt lgkmcnt(7)
	v_mfma_f32_16x16x32_bf16 v[164:167], v[48:51], v[212:215], v[164:167]
	ds_read_b128 v[80:83], v239 offset:22528
	s_waitcnt lgkmcnt(7)
	v_mfma_f32_16x16x32_bf16 v[160:163], v[52:55], v[212:215], v[160:163]
	ds_read_b128 v[84:87], v239 offset:24576
	s_waitcnt lgkmcnt(7)
	v_mfma_f32_16x16x32_bf16 v[156:159], v[56:59], v[212:215], v[156:159]
	ds_read_b128 v[88:91], v239 offset:26624
	s_waitcnt lgkmcnt(7)
	v_mfma_f32_16x16x32_bf16 v[152:155], v[60:63], v[212:215], v[152:155]
	ds_read_b128 v[92:95], v239 offset:28672
	s_waitcnt lgkmcnt(7)
	v_mfma_f32_16x16x32_bf16 v[148:151], v[64:67], v[212:215], v[148:151]
	ds_read_b128 v[96:99], v239 offset:30720
	s_waitcnt lgkmcnt(7)
	v_mfma_f32_16x16x32_bf16 v[144:147], v[68:71], v[212:215], v[144:147]
	s_waitcnt lgkmcnt(6)
	v_mfma_f32_16x16x32_bf16 v[140:143], v[72:75], v[212:215], v[140:143]
	s_waitcnt lgkmcnt(5)
	v_mfma_f32_16x16x32_bf16 v[136:139], v[76:79], v[212:215], v[136:139]
	s_waitcnt lgkmcnt(4)
	v_mfma_f32_16x16x32_bf16 v[132:135], v[80:83], v[212:215], v[132:135]
	s_waitcnt lgkmcnt(3)
	v_mfma_f32_16x16x32_bf16 v[128:131], v[84:87], v[212:215], v[128:131]
	s_waitcnt lgkmcnt(2)
	v_mfma_f32_16x16x32_bf16 v[124:127], v[88:91], v[212:215], v[124:127]
	s_waitcnt lgkmcnt(1)
	v_mfma_f32_16x16x32_bf16 v[120:123], v[92:95], v[212:215], v[120:123]
	s_waitcnt lgkmcnt(0)
	v_mfma_f32_16x16x32_bf16 v[116:119], v[96:99], v[212:215], v[116:119]
; #define LAS __attribute__((address_space(3)))
; #define LOADV(i) do { _Pragma("unroll") for (int j = 0; j < 4; ++j) st[j] = *(const u32x4*)(vbase + (j * 64 * 256 + (i) * 64) + voff); } while (0)
; #define STOREV() do { _Pragma("unroll") for (int j = 0; j < 4; ++j) *(LAS u32x4*)(vst + j * 64 * 144) = st[j]; } while (0)
; __device__ __forceinline__ void ph_attn(const Params& p, LAS unsigned char* lds) {
;     ...
; #pragma unroll 1
;         for (int i = 0; i < 4; ++i) {
;             __syncthreads(); STOREV(); __syncthreads();
;             if (i < 3) LOADV(i + 1);
;             if (active) {
; #pragma unroll
;                 for (int ks = 0; ks < 2; ++ks) {
;                     const bf16x8 pf = *(const LAS bf16x8*)(pw + fq * 8 + i * 128 + ks * 64);
; #pragma unroll
;                     for (int dt = 0; dt < 16; ++dt) {
;                         const bf16x8 vf = *(const LAS bf16x8*)(vrd + dt * 16 * 144 + ks * 64);
;                         oa[dt] = __builtin_amdgcn_mfma_f32_16x16x32_bf16(vf, pf, oa[dt], 0, 0, 0);
;                     }
;                 }
.Lat_pv1:
	s_waitcnt lgkmcnt(0)
	s_barrier
	s_waitcnt vmcnt(7)
	ds_write_b128 v199, v[100:103]
	s_waitcnt vmcnt(6)
	ds_write_b128 v199, v[104:107] offset:8192
	s_waitcnt vmcnt(5)
	ds_write_b128 v199, v[108:111] offset:16384
	s_waitcnt vmcnt(4)
	ds_write_b128 v199, v[112:115] offset:24576
	s_and_b64 vcc, exec, s[4:5]
	s_cbranch_vccnz .Lat_pv2
	ds_read_b128 v[208:211], v187 offset:128
	ds_read_b128 v[212:215], v187 offset:192
	ds_read_b128 v[36:39], v4
	ds_read_b128 v[40:43], v4 offset:2048
	ds_read_b128 v[44:47], v4 offset:4096
	ds_read_b128 v[48:51], v4 offset:6144
	ds_read_b128 v[52:55], v4 offset:8192
	ds_read_b128 v[56:59], v4 offset:10240
	ds_read_b128 v[60:63], v4 offset:12288
	ds_read_b128 v[64:67], v4 offset:14336
	s_waitcnt lgkmcnt(7)
	v_mfma_f32_16x16x32_bf16 v[176:179], v[36:39], v[208:211], v[176:179]
	ds_read_b128 v[68:71], v4 offset:26640
	s_waitcnt lgkmcnt(7)
	v_mfma_f32_16x16x32_bf16 v[172:175], v[40:43], v[208:211], v[172:175]
	ds_read_b128 v[72:75], v4 offset:28688
	s_waitcnt lgkmcnt(7)
	v_mfma_f32_16x16x32_bf16 v[168:171], v[44:47], v[208:211], v[168:171]
	ds_read_b128 v[76:79], v4 offset:30736
	s_waitcnt lgkmcnt(7)
	v_mfma_f32_16x16x32_bf16 v[164:167], v[48:51], v[208:211], v[164:167]
	ds_read_b128 v[80:83], v4 offset:32784
	s_waitcnt lgkmcnt(7)
	v_mfma_f32_16x16x32_bf16 v[160:163], v[52:55], v[208:211], v[160:163]
	ds_read_b128 v[84:87], v4 offset:34832
	s_waitcnt lgkmcnt(7)
	v_mfma_f32_16x16x32_bf16 v[156:159], v[56:59], v[208:211], v[156:159]
	ds_read_b128 v[88:91], v4 offset:36880
	s_waitcnt lgkmcnt(7)
	v_mfma_f32_16x16x32_bf16 v[152:155], v[60:63], v[208:211], v[152:155]
	ds_read_b128 v[92:95], v4 offset:38928
	s_waitcnt lgkmcnt(7)
	v_mfma_f32_16x16x32_bf16 v[148:151], v[64:67], v[208:211], v[148:151]
	ds_read_b128 v[96:99], v4 offset:40976
	s_waitcnt lgkmcnt(7)
	v_mfma_f32_16x16x32_bf16 v[144:147], v[68:71], v[208:211], v[144:147]
	ds_read_b128 v[36:39], v5
	s_waitcnt lgkmcnt(7)
	v_mfma_f32_16x16x32_bf16 v[140:143], v[72:75], v[208:211], v[140:143]
	ds_read_b128 v[40:43], v5 offset:2048
	s_waitcnt lgkmcnt(7)
	v_mfma_f32_16x16x32_bf16 v[136:139], v[76:79], v[208:211], v[136:139]
	ds_read_b128 v[44:47], v5 offset:4096
	s_waitcnt lgkmcnt(7)
	v_mfma_f32_16x16x32_bf16 v[132:135], v[80:83], v[208:211], v[132:135]
	ds_read_b128 v[48:51], v5 offset:6144
	s_waitcnt lgkmcnt(7)
	v_mfma_f32_16x16x32_bf16 v[128:131], v[84:87], v[208:211], v[128:131]
	ds_read_b128 v[52:55], v5 offset:8192
	s_waitcnt lgkmcnt(7)
	v_mfma_f32_16x16x32_bf16 v[124:127], v[88:91], v[208:211], v[124:127]
	ds_read_b128 v[56:59], v5 offset:10240
	s_waitcnt lgkmcnt(7)
	v_mfma_f32_16x16x32_bf16 v[120:123], v[92:95], v[208:211], v[120:123]
	ds_read_b128 v[60:63], v5 offset:12288
	s_waitcnt lgkmcnt(7)
	v_mfma_f32_16x16x32_bf16 v[116:119], v[96:99], v[208:211], v[116:119]
	ds_read_b128 v[64:67], v5 offset:14336
	s_waitcnt lgkmcnt(7)
	v_mfma_f32_16x16x32_bf16 v[176:179], v[36:39], v[212:215], v[176:179]
	ds_read_b128 v[68:71], v5 offset:26640
	s_waitcnt lgkmcnt(7)
	v_mfma_f32_16x16x32_bf16 v[172:175], v[40:43], v[212:215], v[172:175]
	ds_read_b128 v[72:75], v5 offset:28688
	s_waitcnt lgkmcnt(7)
	v_mfma_f32_16x16x32_bf16 v[168:171], v[44:47], v[212:215], v[168:171]
	ds_read_b128 v[76:79], v5 offset:30736
	s_waitcnt lgkmcnt(7)
	v_mfma_f32_16x16x32_bf16 v[164:167], v[48:51], v[212:215], v[164:167]
	ds_read_b128 v[80:83], v5 offset:32784
	s_waitcnt lgkmcnt(7)
	v_mfma_f32_16x16x32_bf16 v[160:163], v[52:55], v[212:215], v[160:163]
	ds_read_b128 v[84:87], v5 offset:34832
	s_waitcnt lgkmcnt(7)
	v_mfma_f32_16x16x32_bf16 v[156:159], v[56:59], v[212:215], v[156:159]
	ds_read_b128 v[88:91], v5 offset:36880
	s_waitcnt lgkmcnt(7)
	v_mfma_f32_16x16x32_bf16 v[152:155], v[60:63], v[212:215], v[152:155]
	ds_read_b128 v[92:95], v5 offset:38928
	s_waitcnt lgkmcnt(7)
	v_mfma_f32_16x16x32_bf16 v[148:151], v[64:67], v[212:215], v[148:151]
	ds_read_b128 v[96:99], v5 offset:40976
	s_waitcnt lgkmcnt(7)
	v_mfma_f32_16x16x32_bf16 v[144:147], v[68:71], v[212:215], v[144:147]
	s_waitcnt lgkmcnt(6)
	v_mfma_f32_16x16x32_bf16 v[140:143], v[72:75], v[212:215], v[140:143]
	s_waitcnt lgkmcnt(5)
	v_mfma_f32_16x16x32_bf16 v[136:139], v[76:79], v[212:215], v[136:139]
	s_waitcnt lgkmcnt(4)
	v_mfma_f32_16x16x32_bf16 v[132:135], v[80:83], v[212:215], v[132:135]
	s_waitcnt lgkmcnt(3)
	v_mfma_f32_16x16x32_bf16 v[128:131], v[84:87], v[212:215], v[128:131]
	s_waitcnt lgkmcnt(2)
	v_mfma_f32_16x16x32_bf16 v[124:127], v[88:91], v[212:215], v[124:127]
	s_waitcnt lgkmcnt(1)
	v_mfma_f32_16x16x32_bf16 v[120:123], v[92:95], v[212:215], v[120:123]
	s_waitcnt lgkmcnt(0)
	v_mfma_f32_16x16x32_bf16 v[116:119], v[96:99], v[212:215], v[116:119]
; #define LAS __attribute__((address_space(3)))
; #define LOADV(i) do { _Pragma("unroll") for (int j = 0; j < 4; ++j) st[j] = *(const u32x4*)(vbase + (j * 64 * 256 + (i) * 64) + voff); } while (0)
; #define STOREV() do { _Pragma("unroll") for (int j = 0; j < 4; ++j) *(LAS u32x4*)(vst + j * 64 * 144) = st[j]; } while (0)
; __device__ __forceinline__ void ph_attn(const Params& p, LAS unsigned char* lds) {
;     ...
; #pragma unroll 1
;         for (int i = 0; i < 4; ++i) {
;             __syncthreads(); STOREV(); __syncthreads();
;             if (i < 3) LOADV(i + 1);
;             if (active) {
; #pragma unroll
;                 for (int ks = 0; ks < 2; ++ks) {
;                     const bf16x8 pf = *(const LAS bf16x8*)(pw + fq * 8 + i * 128 + ks * 64);
; #pragma unroll
;                     for (int dt = 0; dt < 16; ++dt) {
;                         const bf16x8 vf = *(const LAS bf16x8*)(vrd + dt * 16 * 144 + ks * 64);
;                         oa[dt] = __builtin_amdgcn_mfma_f32_16x16x32_bf16(vf, pf, oa[dt], 0, 0, 0);
;                     }
;                 }
.Lat_pv2:
	s_waitcnt lgkmcnt(0)
	s_barrier
	s_waitcnt vmcnt(3)
	ds_write_b128 v6, v[240:243]
	s_waitcnt vmcnt(2)
	ds_write_b128 v6, v[244:247] offset:8192
	s_waitcnt vmcnt(1)
	ds_write_b128 v6, v[248:251] offset:26640
	s_waitcnt vmcnt(0)
	ds_write_b128 v6, v[252:255] offset:34832
	s_and_b64 vcc, exec, s[4:5]
	s_cbranch_vccnz .Lat_pv3
	ds_read_b128 v[208:211], v187 offset:256
	ds_read_b128 v[212:215], v187 offset:320
	ds_read_b128 v[36:39], v201
	ds_read_b128 v[40:43], v201 offset:2048
	ds_read_b128 v[44:47], v201 offset:4096
	ds_read_b128 v[48:51], v201 offset:6144
	ds_read_b128 v[52:55], v201 offset:8192
	ds_read_b128 v[56:59], v201 offset:10240
	ds_read_b128 v[60:63], v201 offset:12288
	ds_read_b128 v[64:67], v201 offset:14336
	s_waitcnt lgkmcnt(7)
	v_mfma_f32_16x16x32_bf16 v[176:179], v[36:39], v[208:211], v[176:179]
	ds_read_b128 v[68:71], v201 offset:16384
	s_waitcnt lgkmcnt(7)
	v_mfma_f32_16x16x32_bf16 v[172:175], v[40:43], v[208:211], v[172:175]
	ds_read_b128 v[72:75], v201 offset:18432
	s_waitcnt lgkmcnt(7)
	v_mfma_f32_16x16x32_bf16 v[168:171], v[44:47], v[208:211], v[168:171]
	ds_read_b128 v[76:79], v201 offset:20480
	s_waitcnt lgkmcnt(7)
	v_mfma_f32_16x16x32_bf16 v[164:167], v[48:51], v[208:211], v[164:167]
	ds_read_b128 v[80:83], v201 offset:22528
	s_waitcnt lgkmcnt(7)
	v_mfma_f32_16x16x32_bf16 v[160:163], v[52:55], v[208:211], v[160:163]
	ds_read_b128 v[84:87], v201 offset:24576
	s_waitcnt lgkmcnt(7)
	v_mfma_f32_16x16x32_bf16 v[156:159], v[56:59], v[208:211], v[156:159]
	ds_read_b128 v[88:91], v201 offset:26624
	s_waitcnt lgkmcnt(7)
	v_mfma_f32_16x16x32_bf16 v[152:155], v[60:63], v[208:211], v[152:155]
	ds_read_b128 v[92:95], v201 offset:28672
	s_waitcnt lgkmcnt(7)
	v_mfma_f32_16x16x32_bf16 v[148:151], v[64:67], v[208:211], v[148:151]
	ds_read_b128 v[96:99], v201 offset:30720
	s_waitcnt lgkmcnt(7)
	v_mfma_f32_16x16x32_bf16 v[144:147], v[68:71], v[208:211], v[144:147]
	ds_read_b128 v[36:39], v239
	s_waitcnt lgkmcnt(7)
	v_mfma_f32_16x16x32_bf16 v[140:143], v[72:75], v[208:211], v[140:143]
	ds_read_b128 v[40:43], v239 offset:2048
	s_waitcnt lgkmcnt(7)
	v_mfma_f32_16x16x32_bf16 v[136:139], v[76:79], v[208:211], v[136:139]
	ds_read_b128 v[44:47], v239 offset:4096
	s_waitcnt lgkmcnt(7)
	v_mfma_f32_16x16x32_bf16 v[132:135], v[80:83], v[208:211], v[132:135]
	ds_read_b128 v[48:51], v239 offset:6144
	s_waitcnt lgkmcnt(7)
	v_mfma_f32_16x16x32_bf16 v[128:131], v[84:87], v[208:211], v[128:131]
	ds_read_b128 v[52:55], v239 offset:8192
	s_waitcnt lgkmcnt(7)
	v_mfma_f32_16x16x32_bf16 v[124:127], v[88:91], v[208:211], v[124:127]
	ds_read_b128 v[56:59], v239 offset:10240
	s_waitcnt lgkmcnt(7)
	v_mfma_f32_16x16x32_bf16 v[120:123], v[92:95], v[208:211], v[120:123]
	ds_read_b128 v[60:63], v239 offset:12288
	s_waitcnt lgkmcnt(7)
	v_mfma_f32_16x16x32_bf16 v[116:119], v[96:99], v[208:211], v[116:119]
	ds_read_b128 v[64:67], v239 offset:14336
	s_waitcnt lgkmcnt(7)
	v_mfma_f32_16x16x32_bf16 v[176:179], v[36:39], v[212:215], v[176:179]
	ds_read_b128 v[68:71], v239 offset:16384
	s_waitcnt lgkmcnt(7)
	v_mfma_f32_16x16x32_bf16 v[172:175], v[40:43], v[212:215], v[172:175]
	ds_read_b128 v[72:75], v239 offset:18432
	s_waitcnt lgkmcnt(7)
	v_mfma_f32_16x16x32_bf16 v[168:171], v[44:47], v[212:215], v[168:171]
	ds_read_b128 v[76:79], v239 offset:20480
	s_waitcnt lgkmcnt(7)
	v_mfma_f32_16x16x32_bf16 v[164:167], v[48:51], v[212:215], v[164:167]
	ds_read_b128 v[80:83], v239 offset:22528
	s_waitcnt lgkmcnt(7)
	v_mfma_f32_16x16x32_bf16 v[160:163], v[52:55], v[212:215], v[160:163]
	ds_read_b128 v[84:87], v239 offset:24576
	s_waitcnt lgkmcnt(7)
	v_mfma_f32_16x16x32_bf16 v[156:159], v[56:59], v[212:215], v[156:159]
	ds_read_b128 v[88:91], v239 offset:26624
	s_waitcnt lgkmcnt(7)
	v_mfma_f32_16x16x32_bf16 v[152:155], v[60:63], v[212:215], v[152:155]
	ds_read_b128 v[92:95], v239 offset:28672
	s_waitcnt lgkmcnt(7)
	v_mfma_f32_16x16x32_bf16 v[148:151], v[64:67], v[212:215], v[148:151]
	ds_read_b128 v[96:99], v239 offset:30720
	s_waitcnt lgkmcnt(7)
	v_mfma_f32_16x16x32_bf16 v[144:147], v[68:71], v[212:215], v[144:147]
	s_waitcnt lgkmcnt(6)
	v_mfma_f32_16x16x32_bf16 v[140:143], v[72:75], v[212:215], v[140:143]
	s_waitcnt lgkmcnt(5)
	v_mfma_f32_16x16x32_bf16 v[136:139], v[76:79], v[212:215], v[136:139]
	s_waitcnt lgkmcnt(4)
	v_mfma_f32_16x16x32_bf16 v[132:135], v[80:83], v[212:215], v[132:135]
	s_waitcnt lgkmcnt(3)
	v_mfma_f32_16x16x32_bf16 v[128:131], v[84:87], v[212:215], v[128:131]
	s_waitcnt lgkmcnt(2)
	v_mfma_f32_16x16x32_bf16 v[124:127], v[88:91], v[212:215], v[124:127]
	s_waitcnt lgkmcnt(1)
	v_mfma_f32_16x16x32_bf16 v[120:123], v[92:95], v[212:215], v[120:123]
	s_waitcnt lgkmcnt(0)
	v_mfma_f32_16x16x32_bf16 v[116:119], v[96:99], v[212:215], v[116:119]
; #define LAS __attribute__((address_space(3)))
; #define LOADV(i) do { _Pragma("unroll") for (int j = 0; j < 4; ++j) st[j] = *(const u32x4*)(vbase + (j * 64 * 256 + (i) * 64) + voff); } while (0)
; #define STOREV() do { _Pragma("unroll") for (int j = 0; j < 4; ++j) *(LAS u32x4*)(vst + j * 64 * 144) = st[j]; } while (0)
; __device__ __forceinline__ void ph_attn(const Params& p, LAS unsigned char* lds) {
;     ...
; #pragma unroll 1
;         for (int i = 0; i < 4; ++i) {
;             __syncthreads(); STOREV(); __syncthreads();
;             if (i < 3) LOADV(i + 1);
;             if (active) {
; #pragma unroll
;                 for (int ks = 0; ks < 2; ++ks) {
;                     const bf16x8 pf = *(const LAS bf16x8*)(pw + fq * 8 + i * 128 + ks * 64);
; #pragma unroll
;                     for (int dt = 0; dt < 16; ++dt) {
;                         const bf16x8 vf = *(const LAS bf16x8*)(vrd + dt * 16 * 144 + ks * 64);
;                         oa[dt] = __builtin_amdgcn_mfma_f32_16x16x32_bf16(vf, pf, oa[dt], 0, 0, 0);
;                     }
;                 }
.Lat_pv3:
	s_waitcnt lgkmcnt(0)
	s_barrier
	s_and_b64 vcc, exec, s[4:5]
	s_cbranch_vccnz .LBB0_1108
	ds_read_b128 v[208:211], v187 offset:384
	ds_read_b128 v[212:215], v187 offset:448
	ds_read_b128 v[36:39], v4
	ds_read_b128 v[40:43], v4 offset:2048
	ds_read_b128 v[44:47], v4 offset:4096
	ds_read_b128 v[48:51], v4 offset:6144
	ds_read_b128 v[52:55], v4 offset:8192
	ds_read_b128 v[56:59], v4 offset:10240
	ds_read_b128 v[60:63], v4 offset:12288
	ds_read_b128 v[64:67], v4 offset:14336
	s_waitcnt lgkmcnt(7)
	v_mfma_f32_16x16x32_bf16 v[176:179], v[36:39], v[208:211], v[176:179]
	ds_read_b128 v[68:71], v4 offset:26640
	s_waitcnt lgkmcnt(7)
	v_mfma_f32_16x16x32_bf16 v[172:175], v[40:43], v[208:211], v[172:175]
	ds_read_b128 v[72:75], v4 offset:28688
	s_waitcnt lgkmcnt(7)
	v_mfma_f32_16x16x32_bf16 v[168:171], v[44:47], v[208:211], v[168:171]
	ds_read_b128 v[76:79], v4 offset:30736
	s_waitcnt lgkmcnt(7)
	v_mfma_f32_16x16x32_bf16 v[164:167], v[48:51], v[208:211], v[164:167]
	ds_read_b128 v[80:83], v4 offset:32784
	s_waitcnt lgkmcnt(7)
	v_mfma_f32_16x16x32_bf16 v[160:163], v[52:55], v[208:211], v[160:163]
	ds_read_b128 v[84:87], v4 offset:34832
	s_waitcnt lgkmcnt(7)
	v_mfma_f32_16x16x32_bf16 v[156:159], v[56:59], v[208:211], v[156:159]
	ds_read_b128 v[88:91], v4 offset:36880
	s_waitcnt lgkmcnt(7)
	v_mfma_f32_16x16x32_bf16 v[152:155], v[60:63], v[208:211], v[152:155]
	ds_read_b128 v[92:95], v4 offset:38928
	s_waitcnt lgkmcnt(7)
	v_mfma_f32_16x16x32_bf16 v[148:151], v[64:67], v[208:211], v[148:151]
	ds_read_b128 v[96:99], v4 offset:40976
	s_waitcnt lgkmcnt(7)
	v_mfma_f32_16x16x32_bf16 v[144:147], v[68:71], v[208:211], v[144:147]
	ds_read_b128 v[36:39], v5
	s_waitcnt lgkmcnt(7)
	v_mfma_f32_16x16x32_bf16 v[140:143], v[72:75], v[208:211], v[140:143]
	ds_read_b128 v[40:43], v5 offset:2048
	s_waitcnt lgkmcnt(7)
	v_mfma_f32_16x16x32_bf16 v[136:139], v[76:79], v[208:211], v[136:139]
	ds_read_b128 v[44:47], v5 offset:4096
	s_waitcnt lgkmcnt(7)
	v_mfma_f32_16x16x32_bf16 v[132:135], v[80:83], v[208:211], v[132:135]
	ds_read_b128 v[48:51], v5 offset:6144
	s_waitcnt lgkmcnt(7)
	v_mfma_f32_16x16x32_bf16 v[128:131], v[84:87], v[208:211], v[128:131]
	ds_read_b128 v[52:55], v5 offset:8192
	s_waitcnt lgkmcnt(7)
	v_mfma_f32_16x16x32_bf16 v[124:127], v[88:91], v[208:211], v[124:127]
	ds_read_b128 v[56:59], v5 offset:10240
	s_waitcnt lgkmcnt(7)
	v_mfma_f32_16x16x32_bf16 v[120:123], v[92:95], v[208:211], v[120:123]
	ds_read_b128 v[60:63], v5 offset:12288
	s_waitcnt lgkmcnt(7)
	v_mfma_f32_16x16x32_bf16 v[116:119], v[96:99], v[208:211], v[116:119]
	ds_read_b128 v[64:67], v5 offset:14336
	s_waitcnt lgkmcnt(7)
	v_mfma_f32_16x16x32_bf16 v[176:179], v[36:39], v[212:215], v[176:179]
	ds_read_b128 v[68:71], v5 offset:26640
	s_waitcnt lgkmcnt(7)
	v_mfma_f32_16x16x32_bf16 v[172:175], v[40:43], v[212:215], v[172:175]
	ds_read_b128 v[72:75], v5 offset:28688
	s_waitcnt lgkmcnt(7)
	v_mfma_f32_16x16x32_bf16 v[168:171], v[44:47], v[212:215], v[168:171]
	ds_read_b128 v[76:79], v5 offset:30736
	s_waitcnt lgkmcnt(7)
	v_mfma_f32_16x16x32_bf16 v[164:167], v[48:51], v[212:215], v[164:167]
	ds_read_b128 v[80:83], v5 offset:32784
	s_waitcnt lgkmcnt(7)
	v_mfma_f32_16x16x32_bf16 v[160:163], v[52:55], v[212:215], v[160:163]
	ds_read_b128 v[84:87], v5 offset:34832
	s_waitcnt lgkmcnt(7)
	v_mfma_f32_16x16x32_bf16 v[156:159], v[56:59], v[212:215], v[156:159]
	ds_read_b128 v[88:91], v5 offset:36880
	s_waitcnt lgkmcnt(7)
	v_mfma_f32_16x16x32_bf16 v[152:155], v[60:63], v[212:215], v[152:155]
	ds_read_b128 v[92:95], v5 offset:38928
	s_waitcnt lgkmcnt(7)
	v_mfma_f32_16x16x32_bf16 v[148:151], v[64:67], v[212:215], v[148:151]
	ds_read_b128 v[96:99], v5 offset:40976
	s_waitcnt lgkmcnt(7)
	v_mfma_f32_16x16x32_bf16 v[144:147], v[68:71], v[212:215], v[144:147]
	s_waitcnt lgkmcnt(6)
	v_mfma_f32_16x16x32_bf16 v[140:143], v[72:75], v[212:215], v[140:143]
	s_waitcnt lgkmcnt(5)
	v_mfma_f32_16x16x32_bf16 v[136:139], v[76:79], v[212:215], v[136:139]
	s_waitcnt lgkmcnt(4)
	v_mfma_f32_16x16x32_bf16 v[132:135], v[80:83], v[212:215], v[132:135]
	s_waitcnt lgkmcnt(3)
	v_mfma_f32_16x16x32_bf16 v[128:131], v[84:87], v[212:215], v[128:131]
	s_waitcnt lgkmcnt(2)
	v_mfma_f32_16x16x32_bf16 v[124:127], v[88:91], v[212:215], v[124:127]
	s_waitcnt lgkmcnt(1)
	v_mfma_f32_16x16x32_bf16 v[120:123], v[92:95], v[212:215], v[120:123]
	s_waitcnt lgkmcnt(0)
	v_mfma_f32_16x16x32_bf16 v[116:119], v[96:99], v[212:215], v[116:119]

; #define LAS __attribute__((address_space(3)))
; __global__ void __launch_bounds__(512, 2) mk_fwd(Params p) {
;     extern __shared__ __attribute__((aligned(16))) unsigned char smem[];
;     LAS unsigned char* lds = (LAS unsigned char*)smem;
;     unsigned char* ws = p.ws; const int G = gridDim.x, bid = blockIdx.x;
;     volatile LAS unsigned* st_ = (volatile LAS unsigned*)(lds + 131072);
	.amdhsa_kernel _Z6mk_fwd6Params
		.amdhsa_group_segment_fixed_size 16384
		.amdhsa_private_segment_fixed_size 0
		.amdhsa_kernarg_size 560
		.amdhsa_user_sgpr_count 2
		.amdhsa_user_sgpr_dispatch_ptr 0
		.amdhsa_user_sgpr_queue_ptr 0
		.amdhsa_user_sgpr_kernarg_segment_ptr 1
		.amdhsa_user_sgpr_dispatch_id 0
		.amdhsa_user_sgpr_kernarg_preload_length 0
		.amdhsa_user_sgpr_kernarg_preload_offset 0
		.amdhsa_user_sgpr_private_segment_size 0
		.amdhsa_uses_dynamic_stack 0
		.amdhsa_enable_private_segment 0
		.amdhsa_system_sgpr_workgroup_id_x 1
		.amdhsa_system_sgpr_workgroup_id_y 0
		.amdhsa_system_sgpr_workgroup_id_z 0
		.amdhsa_system_sgpr_workgroup_info 0
		.amdhsa_system_vgpr_workitem_id 2
		.amdhsa_next_free_vgpr 256
		.amdhsa_next_free_sgpr 102
		.amdhsa_accum_offset 256
		.amdhsa_reserve_vcc 1
		.amdhsa_float_round_mode_32 0
		.amdhsa_float_round_mode_16_64 0
		.amdhsa_float_denorm_mode_32 3
		.amdhsa_float_denorm_mode_16_64 3
		.amdhsa_dx10_clamp 1
		.amdhsa_ieee_mode 1
		.amdhsa_fp16_overflow 0
		.amdhsa_tg_split 0
		.amdhsa_exception_fp_ieee_invalid_op 0
		.amdhsa_exception_fp_denorm_src 0
		.amdhsa_exception_fp_ieee_div_zero 0
		.amdhsa_exception_fp_ieee_overflow 0
		.amdhsa_exception_fp_ieee_underflow 0
		.amdhsa_exception_fp_ieee_inexact 0
		.amdhsa_exception_int_div_zero 0
	.end_amdhsa_kernel

; #define LAS __attribute__((address_space(3)))
; __global__ void __launch_bounds__(512, 2) mk_fwd(Params p) {
;     extern __shared__ __attribute__((aligned(16))) unsigned char smem[];
;     LAS unsigned char* lds = (LAS unsigned char*)smem;
amdhsa.kernels:
  - .agpr_count:     0
    .args:
      - .offset:         0
        .size:           304
        .value_kind:     by_value
      - .offset:         304
        .size:           4
        .value_kind:     hidden_block_count_x
      - .offset:         308
        .size:           4
        .value_kind:     hidden_block_count_y
      - .offset:         312
        .size:           4
        .value_kind:     hidden_block_count_z
      - .offset:         316
        .size:           2
        .value_kind:     hidden_group_size_x
      - .offset:         318
        .size:           2
        .value_kind:     hidden_group_size_y
      - .offset:         320
        .size:           2
        .value_kind:     hidden_group_size_z
      - .offset:         322
        .size:           2
        .value_kind:     hidden_remainder_x
      - .offset:         324
        .size:           2
        .value_kind:     hidden_remainder_y
      - .offset:         326
        .size:           2
        .value_kind:     hidden_remainder_z
      - .offset:         344
        .size:           8
        .value_kind:     hidden_global_offset_x
      - .offset:         352
        .size:           8
        .value_kind:     hidden_global_offset_y
      - .offset:         360
        .size:           8
        .value_kind:     hidden_global_offset_z
      - .offset:         368
        .size:           2
        .value_kind:     hidden_grid_dims
      - .offset:         392
        .size:           8
        .value_kind:     hidden_multigrid_sync_arg
      - .offset:         424
        .size:           4
        .value_kind:     hidden_dynamic_lds_size
    .group_segment_fixed_size: 16384
    .kernarg_segment_align: 8
    .kernarg_segment_size: 560
    .language:       OpenCL C
    .language_version:
      - 2
      - 0
    .max_flat_workgroup_size: 512
    .name:           _Z6mk_fwd6Params
    .private_segment_fixed_size: 0
    .sgpr_count:     108
    .sgpr_spill_count: 48
    .symbol:         _Z6mk_fwd6Params.kd
    .uniform_work_group_size: 1
    .uses_dynamic_stack: false
    .vgpr_count:     256
    .vgpr_spill_count: 0
    .wavefront_size: 64
